# stack15: stack10 + K-cache conversions moved out of the conversion phase into idle phase tails (layer 0: input-projection tail, layer 1: layer-0 FFN-up tail)
# speedup vs baseline: 1.0077x; 1.0077x over previous
.LBB0_171:
	s_add_u32 s12, s96, 0x16708000
	s_waitcnt lgkmcnt(0)
	s_mov_b32 s2, 0x200000
	s_addc_u32 s13, s97, 0
	v_cmp_gt_i32_e32 vcc, s2, v16
	s_and_saveexec_b64 s[2:3], vcc
	v_readlane_b32 s10, v250, 43
	s_cbranch_execz .LBB0_174
	s_branch .LBB0_174
	s_load_dwordx2 s[6:7], s[26:27], 0x10
	v_readlane_b32 s4, v250, 58
	v_readlane_b32 s5, v250, 59
	s_lshl_b64 s[8:9], s[4:5], 26
	v_lshlrev_b32_e32 v0, 3, v22
	s_waitcnt lgkmcnt(0)
	s_add_u32 s6, s6, s8
	s_mov_b64 s[4:5], 0
	v_lshl_add_u32 v0, s30, 12, v0
	s_addc_u32 s7, s7, s9
	v_mov_b32_e32 v1, v16

.LBB0_589:
	v_readlane_b32 s36, v250, 58
	s_cmp_lg_u32 s36, 0
	s_cbranch_scc1 .Lkcb_done
	s_cmp_gt_u32 s90, 0xa6
	s_cselect_b32 s39, 0xa6, 0
	s_cmp_lt_u32 s21, s39
	s_cbranch_scc1 .Lkcb_done
	s_sub_u32 s36, s21, s39
	s_lshl_b32 s36, s36, 9
	s_sub_u32 s38, s90, s39
	s_lshl_b32 s38, s38, 9
	v_readlane_b32 s44, v250, 52
	v_readlane_b32 s45, v250, 53
	s_nop 4
	s_load_dwordx2 s[46:47], s[44:45], 0x10
	s_add_u32 s42, s96, 0x16708000
	s_addc_u32 s43, s97, 0
	v_add_u32_e32 v0, s36, v224
	s_waitcnt lgkmcnt(0)
.Lkcb_kloop:
	v_add_u32_e32 v1, s38, v0
	v_add_u32_e32 v2, s38, v1
	v_add_u32_e32 v3, s38, v2
	v_min_u32_e32 v4, 0x1fffff, v0
	v_lshlrev_b32_e32 v4, 5, v4
	v_min_u32_e32 v5, 0x1fffff, v1
	v_lshlrev_b32_e32 v5, 5, v5
	v_min_u32_e32 v6, 0x1fffff, v2
	v_lshlrev_b32_e32 v6, 5, v6
	v_min_u32_e32 v7, 0x1fffff, v3
	v_lshlrev_b32_e32 v7, 5, v7
	global_load_dwordx4 v[32:35], v4, s[46:47]
	global_load_dwordx4 v[36:39], v4, s[46:47] offset:16
	global_load_dwordx4 v[40:43], v5, s[46:47]
	global_load_dwordx4 v[44:47], v5, s[46:47] offset:16
	global_load_dwordx4 v[48:51], v6, s[46:47]
	global_load_dwordx4 v[52:55], v6, s[46:47] offset:16
	global_load_dwordx4 v[56:59], v7, s[46:47]
	global_load_dwordx4 v[60:63], v7, s[46:47] offset:16
	v_lshrrev_b32_e32 v8, 6, v0
	v_lshrrev_b32_e32 v9, 18, v0
	v_lshl_add_u32 v8, v9, 6, v8
	v_and_b32_e32 v9, 63, v0
	v_lshlrev_b32_e32 v9, 4, v9
	v_lshl_add_u32 v12, v8, 10, v9
	v_lshrrev_b32_e32 v8, 6, v1
	v_lshrrev_b32_e32 v9, 18, v1
	v_lshl_add_u32 v8, v9, 6, v8
	v_and_b32_e32 v9, 63, v1
	v_lshlrev_b32_e32 v9, 4, v9
	v_lshl_add_u32 v13, v8, 10, v9
	v_lshrrev_b32_e32 v8, 6, v2
	v_lshrrev_b32_e32 v9, 18, v2
	v_lshl_add_u32 v8, v9, 6, v8
	v_and_b32_e32 v9, 63, v2
	v_lshlrev_b32_e32 v9, 4, v9
	v_lshl_add_u32 v14, v8, 10, v9
	v_lshrrev_b32_e32 v8, 6, v3
	v_lshrrev_b32_e32 v9, 18, v3
	v_lshl_add_u32 v8, v9, 6, v8
	v_and_b32_e32 v9, 63, v3
	v_lshlrev_b32_e32 v9, 4, v9
	v_lshl_add_u32 v15, v8, 10, v9
	s_waitcnt vmcnt(6)
	v_cvt_pk_bf16_f32 v32, v32, v33
	v_cvt_pk_bf16_f32 v33, v34, v35
	v_cvt_pk_bf16_f32 v34, v36, v37
	v_cvt_pk_bf16_f32 v35, v38, v39
	v_cmp_gt_u32_e32 vcc, 0x200000, v0
	s_and_saveexec_b64 s[44:45], vcc
	global_store_dwordx4 v12, v[32:35], s[42:43]
	s_mov_b64 exec, s[44:45]
	s_waitcnt vmcnt(4)
	v_cvt_pk_bf16_f32 v40, v40, v41
	v_cvt_pk_bf16_f32 v41, v42, v43
	v_cvt_pk_bf16_f32 v42, v44, v45
	v_cvt_pk_bf16_f32 v43, v46, v47
	v_cmp_gt_u32_e32 vcc, 0x200000, v1
	s_and_saveexec_b64 s[44:45], vcc
	global_store_dwordx4 v13, v[40:43], s[42:43]
	s_mov_b64 exec, s[44:45]
	s_waitcnt vmcnt(2)
	v_cvt_pk_bf16_f32 v48, v48, v49
	v_cvt_pk_bf16_f32 v49, v50, v51
	v_cvt_pk_bf16_f32 v50, v52, v53
	v_cvt_pk_bf16_f32 v51, v54, v55
	v_cmp_gt_u32_e32 vcc, 0x200000, v2
	s_and_saveexec_b64 s[44:45], vcc
	global_store_dwordx4 v14, v[48:51], s[42:43]
	s_mov_b64 exec, s[44:45]
	s_waitcnt vmcnt(0)
	v_cvt_pk_bf16_f32 v56, v56, v57
	v_cvt_pk_bf16_f32 v57, v58, v59
	v_cvt_pk_bf16_f32 v58, v60, v61
	v_cvt_pk_bf16_f32 v59, v62, v63
	v_cmp_gt_u32_e32 vcc, 0x200000, v3
	s_and_saveexec_b64 s[44:45], vcc
	global_store_dwordx4 v15, v[56:59], s[42:43]
	s_mov_b64 exec, s[44:45]
	v_add_u32_e32 v0, s38, v3
	s_nop 1
	v_readfirstlane_b32 s36, v0
	s_cmp_lt_u32 s36, 0x200000
	s_cbranch_scc1 .Lkcb_kloop
